# baseline (speedup 1.0000x reference)
; #define STAGE(P, GP, ktrel) do { const GAS char* _g = (GP) + (ktrel) * (BK * 2); \
;     __builtin_amdgcn_global_load_lds((const GAS unsigned*)(_g + so0), (unsigned*)((char*)(P) + tid_ * 16), 16, 0, 0); \
;     __builtin_amdgcn_global_load_lds((const GAS unsigned*)(_g + so1), (unsigned*)((char*)(P) + tid_ * 16 + 8192), 16, 0, 0); } while (0)
; #define WAIT_V(n) asm volatile("s_waitcnt vmcnt(" #n ")" ::: "memory")
; #define WAIT_L(n) asm volatile("s_waitcnt lgkmcnt(" #n ")" ::: "memory")
; #define BAR __builtin_amdgcn_s_barrier()
; #define SCHED __builtin_amdgcn_sched_barrier(0)
; #define LDA(dst, b, h) for (int m = 0; m < 4; ++m) for (int k = 0; k < 2; ++k) \
;     dst[m][k] = *reinterpret_cast<const bf16x8*>((char*)SA(b, h) + lds_byte(wr * 64 + m * 16 + fr, k * 32 + fq * 8))
; #define LDB(dst, b, h) for (int n = 0; n < 2; ++n) for (int k = 0; k < 2; ++k) \
;     dst[n][k] = *reinterpret_cast<const bf16x8*>((char*)SB(b, h) + lds_byte(wc * 32 + n * 16 + fr, k * 32 + fq * 8))
; #define MMA(ai, bj, At_, Bt_) do { __builtin_amdgcn_s_setprio(1); \
;     for (int m = 0; m < 4; ++m) for (int n = 0; n < 2; ++n) for (int k = 0; k < 2; ++k) \
;       acc[ai][bj][m][n] = __builtin_amdgcn_mfma_f32_16x16x32_bf16(At_[m][k], Bt_[n][k], acc[ai][bj][m][n], 0, 0, 0); \
;     __builtin_amdgcn_s_setprio(0); } while (0)
; template <int K, int LD = K>
; __device__ __forceinline__ void gemm_main(const GAS bf16* A, const GAS bf16* Bt, int brow, int bcol, f32x4 (&acc)[2][2][4][2]) {
;     ...
;   for (int t = 0; t < nt - 2; t += 2) {
;     LDB(B0, 0, 0); SCHED; LDA(At, 0, 0); STAGE(SA(1, 1), pA1, 1);
;     WAIT_L(8); BAR; WAIT_L(0); MMA(0, 0, At, B0); BAR; SCHED;
;     LDB(B1, 0, 1); STAGE(SB(0, 0), pB0, 2);
;     BAR; WAIT_L(0); MMA(0, 1, At, B1); BAR;
;     LDA(At, 0, 1); STAGE(SA(0, 0), pA0, 2);
;     BAR; WAIT_L(0); MMA(1, 0, At, B0); BAR; SCHED;
;     STAGE(SB(0, 1), pB1, 2);
;     WAIT_V(6); BAR; MMA(1, 1, At, B1); BAR;
;     LDB(B0, 1, 0); SCHED; LDA(At, 1, 0); STAGE(SA(0, 1), pA1, 2);
;     WAIT_L(8); BAR; WAIT_L(0); MMA(0, 0, At, B0); BAR; SCHED;
;     LDB(B1, 1, 1); STAGE(SB(1, 0), pB0, 3);
;     BAR; WAIT_L(0); MMA(0, 1, At, B1); BAR;
.LBB0_89:
	ds_read_b128 v[162:165], v144
	ds_read_b128 v[166:169], v144 offset:1024
	ds_read_b128 v[174:177], v144 offset:2048
	ds_read_b128 v[178:181], v144 offset:3072
	v_lshl_add_u64 v[230:231], s[14:15], 0, v[130:131]
	v_readfirstlane_b32 s24, v151
	v_lshl_add_u64 v[214:215], v[230:231], 0, s[8:9]
	s_mov_b32 m0, s24
	v_lshl_add_u64 v[232:233], s[14:15], 0, v[132:133]
	v_readfirstlane_b32 s24, v150
	ds_read_b128 v[182:185], v140
	ds_read_b128 v[186:189], v140 offset:1024
	ds_read_b128 v[190:193], v139
	ds_read_b128 v[194:197], v139 offset:1024
	ds_read_b128 v[198:201], v138
	ds_read_b128 v[202:205], v138 offset:1024
	ds_read_b128 v[206:209], v137
	ds_read_b128 v[210:213], v137 offset:1024
	global_load_lds_dwordx4 v[214:215], off
	v_lshl_add_u64 v[214:215], v[232:233], 0, s[8:9]
	s_mov_b32 m0, s24
	s_nop 0
	global_load_lds_dwordx4 v[214:215], off
	s_waitcnt lgkmcnt(8)
	s_waitcnt vmcnt(10)
	s_barrier
	s_waitcnt lgkmcnt(0)
	s_setprio 1
	s_waitcnt lgkmcnt(0)
	v_mfma_f32_16x16x32_bf16 v[126:129], v[162:165], v[182:185], v[126:129]
	v_mfma_f32_16x16x32_bf16 v[122:125], v[174:177], v[182:185], v[122:125]
	v_mfma_f32_16x16x32_bf16 v[118:121], v[162:165], v[190:193], v[118:121]
	v_mfma_f32_16x16x32_bf16 v[114:117], v[174:177], v[190:193], v[114:117]
	v_mfma_f32_16x16x32_bf16 v[110:113], v[162:165], v[198:201], v[110:113]
	v_mfma_f32_16x16x32_bf16 v[106:109], v[174:177], v[198:201], v[106:109]
	v_mfma_f32_16x16x32_bf16 v[102:105], v[162:165], v[206:209], v[102:105]
	v_mfma_f32_16x16x32_bf16 v[98:101], v[174:177], v[206:209], v[98:101]
	v_mfma_f32_16x16x32_bf16 v[126:129], v[166:169], v[186:189], v[126:129]
	v_mfma_f32_16x16x32_bf16 v[122:125], v[178:181], v[186:189], v[122:125]
	v_mfma_f32_16x16x32_bf16 v[118:121], v[166:169], v[194:197], v[118:121]
	v_mfma_f32_16x16x32_bf16 v[114:117], v[178:181], v[194:197], v[114:117]
	v_mfma_f32_16x16x32_bf16 v[110:113], v[166:169], v[202:205], v[110:113]
	v_mfma_f32_16x16x32_bf16 v[106:109], v[178:181], v[202:205], v[106:109]
	v_mfma_f32_16x16x32_bf16 v[102:105], v[166:169], v[210:213], v[102:105]
	v_mfma_f32_16x16x32_bf16 v[98:101], v[178:181], v[210:213], v[98:101]
	s_setprio 0
	s_barrier
	v_lshl_add_u64 v[234:235], s[22:23], 0, v[130:131]
	v_readfirstlane_b32 s24, v146
	v_lshl_add_u64 v[236:237], v[234:235], 0, s[10:11]
	s_mov_b32 m0, s24
	ds_read_b128 v[214:217], v143
	ds_read_b128 v[218:221], v143 offset:1024
	ds_read_b128 v[222:225], v143 offset:2048
	ds_read_b128 v[226:229], v143 offset:3072
	global_load_lds_dwordx4 v[236:237], off
	v_lshl_add_u64 v[236:237], s[22:23], 0, v[132:133]
	v_readfirstlane_b32 s24, v157
	v_lshl_add_u64 v[238:239], v[236:237], 0, s[10:11]
	s_mov_b32 m0, s24
	s_add_u32 s22, s22, 0x100
	global_load_lds_dwordx4 v[238:239], off
	s_waitcnt vmcnt(10)
	s_barrier
	s_waitcnt lgkmcnt(0)
	s_addc_u32 s23, s23, 0
	s_setprio 1
	s_waitcnt lgkmcnt(0)
	v_mfma_f32_16x16x32_bf16 v[94:97], v[214:217], v[182:185], v[94:97]
	v_mfma_f32_16x16x32_bf16 v[90:93], v[222:225], v[182:185], v[90:93]
	v_mfma_f32_16x16x32_bf16 v[86:89], v[214:217], v[190:193], v[86:89]
	v_mfma_f32_16x16x32_bf16 v[82:85], v[222:225], v[190:193], v[82:85]
	v_mfma_f32_16x16x32_bf16 v[78:81], v[214:217], v[198:201], v[78:81]
	v_mfma_f32_16x16x32_bf16 v[74:77], v[222:225], v[198:201], v[74:77]
	v_mfma_f32_16x16x32_bf16 v[70:73], v[214:217], v[206:209], v[70:73]
	v_mfma_f32_16x16x32_bf16 v[66:69], v[222:225], v[206:209], v[66:69]
	v_mfma_f32_16x16x32_bf16 v[94:97], v[218:221], v[186:189], v[94:97]
	v_mfma_f32_16x16x32_bf16 v[90:93], v[226:229], v[186:189], v[90:93]
	v_mfma_f32_16x16x32_bf16 v[86:89], v[218:221], v[194:197], v[86:89]
	v_mfma_f32_16x16x32_bf16 v[82:85], v[226:229], v[194:197], v[82:85]
	v_mfma_f32_16x16x32_bf16 v[78:81], v[218:221], v[202:205], v[78:81]
	v_mfma_f32_16x16x32_bf16 v[74:77], v[226:229], v[202:205], v[74:77]
	v_mfma_f32_16x16x32_bf16 v[70:73], v[218:221], v[210:213], v[70:73]
	v_mfma_f32_16x16x32_bf16 v[66:69], v[226:229], v[210:213], v[66:69]
	s_setprio 0
	v_lshl_add_u64 v[238:239], s[20:21], 0, v[130:131]
	v_readfirstlane_b32 s24, v145
	v_lshl_add_u64 v[240:241], v[238:239], 0, s[10:11]
	s_mov_b32 m0, s24
	s_barrier
	ds_read_b128 v[182:185], v140 offset:16384
	ds_read_b128 v[186:189], v140 offset:17408
	ds_read_b128 v[190:193], v139 offset:16384
	ds_read_b128 v[194:197], v139 offset:17408
	ds_read_b128 v[198:201], v138 offset:16384
	ds_read_b128 v[202:205], v138 offset:17408
	ds_read_b128 v[206:209], v137 offset:16384
	ds_read_b128 v[210:213], v137 offset:17408
	global_load_lds_dwordx4 v[240:241], off
	v_lshl_add_u64 v[240:241], s[20:21], 0, v[132:133]
	v_readfirstlane_b32 s24, v152
	v_lshl_add_u64 v[242:243], v[240:241], 0, s[10:11]
	s_mov_b32 m0, s24
	s_add_u32 s20, s20, 0x100
	global_load_lds_dwordx4 v[242:243], off
	s_barrier
	s_waitcnt lgkmcnt(0)
	s_addc_u32 s21, s21, 0
	s_setprio 1
	s_waitcnt lgkmcnt(0)
	v_mfma_f32_16x16x32_bf16 v[62:65], v[162:165], v[182:185], v[62:65]
	v_mfma_f32_16x16x32_bf16 v[58:61], v[174:177], v[182:185], v[58:61]
	v_mfma_f32_16x16x32_bf16 v[54:57], v[162:165], v[190:193], v[54:57]
	v_mfma_f32_16x16x32_bf16 v[50:53], v[174:177], v[190:193], v[50:53]
	v_mfma_f32_16x16x32_bf16 v[46:49], v[162:165], v[198:201], v[46:49]
	v_mfma_f32_16x16x32_bf16 v[42:45], v[174:177], v[198:201], v[42:45]
	v_mfma_f32_16x16x32_bf16 v[38:41], v[162:165], v[206:209], v[38:41]
	v_mfma_f32_16x16x32_bf16 v[34:37], v[174:177], v[206:209], v[34:37]
	v_mfma_f32_16x16x32_bf16 v[62:65], v[166:169], v[186:189], v[62:65]
	v_mfma_f32_16x16x32_bf16 v[58:61], v[178:181], v[186:189], v[58:61]
	v_mfma_f32_16x16x32_bf16 v[54:57], v[166:169], v[194:197], v[54:57]
	v_mfma_f32_16x16x32_bf16 v[50:53], v[178:181], v[194:197], v[50:53]
	v_mfma_f32_16x16x32_bf16 v[46:49], v[166:169], v[202:205], v[46:49]
	v_mfma_f32_16x16x32_bf16 v[42:45], v[178:181], v[202:205], v[42:45]
	v_mfma_f32_16x16x32_bf16 v[38:41], v[166:169], v[210:213], v[38:41]
	v_mfma_f32_16x16x32_bf16 v[34:37], v[178:181], v[210:213], v[34:37]
	s_setprio 0
	s_barrier
; #define STAGE(P, GP, ktrel) do { const GAS char* _g = (GP) + (ktrel) * (BK * 2); \
;     __builtin_amdgcn_global_load_lds((const GAS unsigned*)(_g + so0), (unsigned*)((char*)(P) + tid_ * 16), 16, 0, 0); \
;     __builtin_amdgcn_global_load_lds((const GAS unsigned*)(_g + so1), (unsigned*)((char*)(P) + tid_ * 16 + 8192), 16, 0, 0); } while (0)
; #define WAIT_V(n) asm volatile("s_waitcnt vmcnt(" #n ")" ::: "memory")
; #define WAIT_L(n) asm volatile("s_waitcnt lgkmcnt(" #n ")" ::: "memory")
; #define BAR __builtin_amdgcn_s_barrier()
; #define SCHED __builtin_amdgcn_sched_barrier(0)
; #define LDA(dst, b, h) for (int m = 0; m < 4; ++m) for (int k = 0; k < 2; ++k) \
;     dst[m][k] = *reinterpret_cast<const bf16x8*>((char*)SA(b, h) + lds_byte(wr * 64 + m * 16 + fr, k * 32 + fq * 8))
; #define LDB(dst, b, h) for (int n = 0; n < 2; ++n) for (int k = 0; k < 2; ++k) \
;     dst[n][k] = *reinterpret_cast<const bf16x8*>((char*)SB(b, h) + lds_byte(wc * 32 + n * 16 + fr, k * 32 + fq * 8))
; #define MMA(ai, bj, At_, Bt_) do { __builtin_amdgcn_s_setprio(1); \
;     for (int m = 0; m < 4; ++m) for (int n = 0; n < 2; ++n) for (int k = 0; k < 2; ++k) \
;       acc[ai][bj][m][n] = __builtin_amdgcn_mfma_f32_16x16x32_bf16(At_[m][k], Bt_[n][k], acc[ai][bj][m][n], 0, 0, 0); \
;     __builtin_amdgcn_s_setprio(0); } while (0)
; template <int K, int LD = K>
; __device__ __forceinline__ void gemm_main(const GAS bf16* A, const GAS bf16* Bt, int brow, int bcol, f32x4 (&acc)[2][2][4][2]) {
;     ...
;     STAGE(SB(0, 1), pB1, 2);
;     WAIT_V(6); BAR; MMA(1, 1, At, B1); BAR;
;     LDB(B0, 1, 0); SCHED; LDA(At, 1, 0); STAGE(SA(0, 1), pA1, 2);
;     WAIT_L(8); BAR; WAIT_L(0); MMA(0, 0, At, B0); BAR; SCHED;
;     LDB(B1, 1, 1); STAGE(SB(1, 0), pB0, 3);
;     BAR; WAIT_L(0); MMA(0, 1, At, B1); BAR;
;     LDA(At, 1, 1); STAGE(SA(1, 0), pA0, 3);
;     BAR; WAIT_L(0); MMA(1, 0, At, B0); BAR; SCHED;
	v_lshl_add_u64 v[242:243], s[18:19], 0, v[130:131]
	v_readfirstlane_b32 s24, v147
	v_lshl_add_u64 v[162:163], v[242:243], 0, s[10:11]
	s_mov_b32 m0, s24
	v_lshl_add_u64 v[244:245], s[18:19], 0, v[132:133]
	v_readfirstlane_b32 s24, v158
	global_load_lds_dwordx4 v[162:163], off
	v_lshl_add_u64 v[162:163], v[244:245], 0, s[10:11]
	s_mov_b32 m0, s24
	s_add_u32 s18, s18, 0x100
	global_load_lds_dwordx4 v[162:163], off
	s_waitcnt vmcnt(10)
	s_addc_u32 s19, s19, 0
	s_barrier
	s_setprio 1
	v_mfma_f32_16x16x32_bf16 v[30:33], v[214:217], v[182:185], v[30:33]
	v_mfma_f32_16x16x32_bf16 v[26:29], v[222:225], v[182:185], v[26:29]
	v_mfma_f32_16x16x32_bf16 v[22:25], v[214:217], v[190:193], v[22:25]
	v_mfma_f32_16x16x32_bf16 v[18:21], v[222:225], v[190:193], v[18:21]
	v_mfma_f32_16x16x32_bf16 v[14:17], v[214:217], v[198:201], v[14:17]
	v_mfma_f32_16x16x32_bf16 v[10:13], v[222:225], v[198:201], v[10:13]
	v_mfma_f32_16x16x32_bf16 v[6:9], v[214:217], v[206:209], v[6:9]
	v_mfma_f32_16x16x32_bf16 v[2:5], v[222:225], v[206:209], v[2:5]
	v_mfma_f32_16x16x32_bf16 v[30:33], v[218:221], v[186:189], v[30:33]
	v_mfma_f32_16x16x32_bf16 v[26:29], v[226:229], v[186:189], v[26:29]
	v_mfma_f32_16x16x32_bf16 v[22:25], v[218:221], v[194:197], v[22:25]
	v_mfma_f32_16x16x32_bf16 v[18:21], v[226:229], v[194:197], v[18:21]
	v_mfma_f32_16x16x32_bf16 v[14:17], v[218:221], v[202:205], v[14:17]
	v_mfma_f32_16x16x32_bf16 v[10:13], v[226:229], v[202:205], v[10:13]
	v_mfma_f32_16x16x32_bf16 v[6:9], v[218:221], v[210:213], v[6:9]
	v_mfma_f32_16x16x32_bf16 v[2:5], v[226:229], v[210:213], v[2:5]
	s_setprio 0
	s_barrier
	ds_read_b128 v[162:165], v142
	ds_read_b128 v[166:169], v142 offset:1024
	ds_read_b128 v[174:177], v142 offset:2048
	ds_read_b128 v[178:181], v142 offset:3072
	v_readfirstlane_b32 s24, v153
	v_lshl_add_u64 v[214:215], v[230:231], 0, s[10:11]
	s_mov_b32 m0, s24
	v_readfirstlane_b32 s24, v154
	ds_read_b128 v[182:185], v140 offset:32768
	ds_read_b128 v[186:189], v140 offset:33792
	ds_read_b128 v[190:193], v139 offset:32768
	ds_read_b128 v[194:197], v139 offset:33792
	ds_read_b128 v[198:201], v138 offset:32768
	ds_read_b128 v[202:205], v138 offset:33792
	ds_read_b128 v[206:209], v137 offset:32768
	ds_read_b128 v[210:213], v137 offset:33792
	global_load_lds_dwordx4 v[214:215], off
	v_lshl_add_u64 v[214:215], v[232:233], 0, s[10:11]
	s_mov_b32 m0, s24
	s_add_u32 s14, s14, 0x100
	global_load_lds_dwordx4 v[214:215], off
	s_waitcnt lgkmcnt(8)
	s_waitcnt vmcnt(10)
	s_barrier
	s_waitcnt lgkmcnt(0)
	s_addc_u32 s15, s15, 0
	s_setprio 1
	s_waitcnt lgkmcnt(0)
	v_mfma_f32_16x16x32_bf16 v[126:129], v[162:165], v[182:185], v[126:129]
	v_mfma_f32_16x16x32_bf16 v[122:125], v[174:177], v[182:185], v[122:125]
	v_mfma_f32_16x16x32_bf16 v[118:121], v[162:165], v[190:193], v[118:121]
	v_mfma_f32_16x16x32_bf16 v[114:117], v[174:177], v[190:193], v[114:117]
	v_mfma_f32_16x16x32_bf16 v[110:113], v[162:165], v[198:201], v[110:113]
	v_mfma_f32_16x16x32_bf16 v[106:109], v[174:177], v[198:201], v[106:109]
	v_mfma_f32_16x16x32_bf16 v[102:105], v[162:165], v[206:209], v[102:105]
	v_mfma_f32_16x16x32_bf16 v[98:101], v[174:177], v[206:209], v[98:101]
	v_mfma_f32_16x16x32_bf16 v[126:129], v[166:169], v[186:189], v[126:129]
	v_mfma_f32_16x16x32_bf16 v[122:125], v[178:181], v[186:189], v[122:125]
	v_mfma_f32_16x16x32_bf16 v[118:121], v[166:169], v[194:197], v[118:121]
	v_mfma_f32_16x16x32_bf16 v[114:117], v[178:181], v[194:197], v[114:117]
	v_mfma_f32_16x16x32_bf16 v[110:113], v[166:169], v[202:205], v[110:113]
	v_mfma_f32_16x16x32_bf16 v[106:109], v[178:181], v[202:205], v[106:109]
	v_mfma_f32_16x16x32_bf16 v[102:105], v[166:169], v[210:213], v[102:105]
	v_mfma_f32_16x16x32_bf16 v[98:101], v[178:181], v[210:213], v[98:101]
	s_setprio 0
	s_barrier
	v_readfirstlane_b32 s24, v148
	v_lshl_add_u64 v[230:231], v[234:235], 0, s[12:13]
	s_mov_b32 m0, s24
	v_readfirstlane_b32 s24, v159
	ds_read_b128 v[214:217], v141
	ds_read_b128 v[218:221], v141 offset:1024
	ds_read_b128 v[222:225], v141 offset:2048
	ds_read_b128 v[226:229], v141 offset:3072
	global_load_lds_dwordx4 v[230:231], off
	v_lshl_add_u64 v[230:231], v[236:237], 0, s[12:13]
	s_mov_b32 m0, s24
	s_nop 0
	global_load_lds_dwordx4 v[230:231], off
	s_waitcnt vmcnt(10)
	s_barrier
	s_waitcnt lgkmcnt(0)
	s_setprio 1
	s_waitcnt lgkmcnt(0)
	v_mfma_f32_16x16x32_bf16 v[94:97], v[214:217], v[182:185], v[94:97]
	v_mfma_f32_16x16x32_bf16 v[90:93], v[222:225], v[182:185], v[90:93]
	v_mfma_f32_16x16x32_bf16 v[86:89], v[214:217], v[190:193], v[86:89]
	v_mfma_f32_16x16x32_bf16 v[82:85], v[222:225], v[190:193], v[82:85]
	v_mfma_f32_16x16x32_bf16 v[78:81], v[214:217], v[198:201], v[78:81]
	v_mfma_f32_16x16x32_bf16 v[74:77], v[222:225], v[198:201], v[74:77]
	v_mfma_f32_16x16x32_bf16 v[70:73], v[214:217], v[206:209], v[70:73]
	v_mfma_f32_16x16x32_bf16 v[66:69], v[222:225], v[206:209], v[66:69]
	v_mfma_f32_16x16x32_bf16 v[94:97], v[218:221], v[186:189], v[94:97]
	v_mfma_f32_16x16x32_bf16 v[90:93], v[226:229], v[186:189], v[90:93]
	v_mfma_f32_16x16x32_bf16 v[86:89], v[218:221], v[194:197], v[86:89]
	v_mfma_f32_16x16x32_bf16 v[82:85], v[226:229], v[194:197], v[82:85]
	v_mfma_f32_16x16x32_bf16 v[78:81], v[218:221], v[202:205], v[78:81]
	v_mfma_f32_16x16x32_bf16 v[74:77], v[226:229], v[202:205], v[74:77]
	v_mfma_f32_16x16x32_bf16 v[70:73], v[218:221], v[210:213], v[70:73]
	v_mfma_f32_16x16x32_bf16 v[66:69], v[226:229], v[210:213], v[66:69]
	s_setprio 0
	v_readfirstlane_b32 s24, v155
	v_lshl_add_u64 v[230:231], v[238:239], 0, s[12:13]
	s_mov_b32 m0, s24
	v_readfirstlane_b32 s24, v156
	s_barrier
; #define STAGE(P, GP, ktrel) do { const GAS char* _g = (GP) + (ktrel) * (BK * 2); \
;     __builtin_amdgcn_global_load_lds((const GAS unsigned*)(_g + so0), (unsigned*)((char*)(P) + tid_ * 16), 16, 0, 0); \
;     __builtin_amdgcn_global_load_lds((const GAS unsigned*)(_g + so1), (unsigned*)((char*)(P) + tid_ * 16 + 8192), 16, 0, 0); } while (0)
; #define WAIT_V(n) asm volatile("s_waitcnt vmcnt(" #n ")" ::: "memory")
; #define WAIT_L(n) asm volatile("s_waitcnt lgkmcnt(" #n ")" ::: "memory")
; #define BAR __builtin_amdgcn_s_barrier()
; #define SCHED __builtin_amdgcn_sched_barrier(0)
; #define LDA(dst, b, h) for (int m = 0; m < 4; ++m) for (int k = 0; k < 2; ++k) \
;     dst[m][k] = *reinterpret_cast<const bf16x8*>((char*)SA(b, h) + lds_byte(wr * 64 + m * 16 + fr, k * 32 + fq * 8))
; #define LDB(dst, b, h) for (int n = 0; n < 2; ++n) for (int k = 0; k < 2; ++k) \
;     dst[n][k] = *reinterpret_cast<const bf16x8*>((char*)SB(b, h) + lds_byte(wc * 32 + n * 16 + fr, k * 32 + fq * 8))
; #define MMA(ai, bj, At_, Bt_) do { __builtin_amdgcn_s_setprio(1); \
;     for (int m = 0; m < 4; ++m) for (int n = 0; n < 2; ++n) for (int k = 0; k < 2; ++k) \
;       acc[ai][bj][m][n] = __builtin_amdgcn_mfma_f32_16x16x32_bf16(At_[m][k], Bt_[n][k], acc[ai][bj][m][n], 0, 0, 0); \
;     __builtin_amdgcn_s_setprio(0); } while (0)
; __device__ __forceinline__ int ugrid() { return __builtin_amdgcn_readfirstlane((int)gridDim.x); }
; template <int K, int LD = K>
; __device__ __forceinline__ void gemm_main(const GAS bf16* A, const GAS bf16* Bt, int brow, int bcol, f32x4 (&acc)[2][2][4][2]) {
;     ...
;     LDA(At, 1, 1); STAGE(SA(1, 0), pA0, 3);
;     BAR; WAIT_L(0); MMA(1, 0, At, B0); BAR; SCHED;
;     STAGE(SB(1, 1), pB1, 3);
;     WAIT_V(6); BAR; MMA(1, 1, At, B1); BAR;
;     pA0 += 4 * BK; pA1 += 4 * BK; pB0 += 4 * BK; pB1 += 4 * BK;
;     asm volatile("" : "+s"(pA0), "+s"(pA1), "+s"(pB0), "+s"(pB1));
;   }
;   { LDB(B0, 0, 0); LDA(At, 0, 0); STAGE(SA(1, 1), pA1, 1);
;     BAR; WAIT_L(0); MMA(0, 0, At, B0); BAR;
; __device__ __forceinline__ void phase_up(int pass) {
;     ...
;     L += ugrid();
;     if (L < NT_) { tile_coords(L, nN, pm, pn); gemm_prefetch<DM>(A, Wgu, pm * 256, pn * 256); load_rr(ssq, pm * 256, par ^ 1); }
	ds_read_b128 v[182:185], v140 offset:49152
	ds_read_b128 v[186:189], v140 offset:50176
	ds_read_b128 v[190:193], v139 offset:49152
	ds_read_b128 v[194:197], v139 offset:50176
	ds_read_b128 v[198:201], v138 offset:49152
	ds_read_b128 v[202:205], v138 offset:50176
	ds_read_b128 v[206:209], v137 offset:49152
	ds_read_b128 v[210:213], v137 offset:50176
	global_load_lds_dwordx4 v[230:231], off
	v_lshl_add_u64 v[230:231], v[240:241], 0, s[12:13]
	s_mov_b32 m0, s24
	s_nop 0
	global_load_lds_dwordx4 v[230:231], off
	s_barrier
	s_waitcnt lgkmcnt(0)
	s_setprio 1
	s_waitcnt lgkmcnt(0)
	v_mfma_f32_16x16x32_bf16 v[62:65], v[162:165], v[182:185], v[62:65]
	v_mfma_f32_16x16x32_bf16 v[58:61], v[174:177], v[182:185], v[58:61]
	v_mfma_f32_16x16x32_bf16 v[54:57], v[162:165], v[190:193], v[54:57]
	v_mfma_f32_16x16x32_bf16 v[50:53], v[174:177], v[190:193], v[50:53]
	v_mfma_f32_16x16x32_bf16 v[46:49], v[162:165], v[198:201], v[46:49]
	v_mfma_f32_16x16x32_bf16 v[42:45], v[174:177], v[198:201], v[42:45]
	v_mfma_f32_16x16x32_bf16 v[38:41], v[162:165], v[206:209], v[38:41]
	v_mfma_f32_16x16x32_bf16 v[34:37], v[174:177], v[206:209], v[34:37]
	v_mfma_f32_16x16x32_bf16 v[62:65], v[166:169], v[186:189], v[62:65]
	v_mfma_f32_16x16x32_bf16 v[58:61], v[178:181], v[186:189], v[58:61]
	v_mfma_f32_16x16x32_bf16 v[54:57], v[166:169], v[194:197], v[54:57]
	v_mfma_f32_16x16x32_bf16 v[50:53], v[178:181], v[194:197], v[50:53]
	v_mfma_f32_16x16x32_bf16 v[46:49], v[166:169], v[202:205], v[46:49]
	v_mfma_f32_16x16x32_bf16 v[42:45], v[178:181], v[202:205], v[42:45]
	v_mfma_f32_16x16x32_bf16 v[38:41], v[166:169], v[210:213], v[38:41]
	v_mfma_f32_16x16x32_bf16 v[34:37], v[178:181], v[210:213], v[34:37]
	s_setprio 0
	s_barrier
	v_readfirstlane_b32 s24, v149
	v_lshl_add_u64 v[162:163], v[242:243], 0, s[12:13]
	s_mov_b32 m0, s24
	v_readfirstlane_b32 s24, v160
	global_load_lds_dwordx4 v[162:163], off
	v_lshl_add_u64 v[162:163], v[244:245], 0, s[12:13]
	s_mov_b32 m0, s24
	s_nop 0
	global_load_lds_dwordx4 v[162:163], off
	s_waitcnt vmcnt(10)
	s_barrier
	s_setprio 1
	v_mfma_f32_16x16x32_bf16 v[30:33], v[214:217], v[182:185], v[30:33]
	v_mfma_f32_16x16x32_bf16 v[26:29], v[222:225], v[182:185], v[26:29]
	v_mfma_f32_16x16x32_bf16 v[22:25], v[214:217], v[190:193], v[22:25]
	v_mfma_f32_16x16x32_bf16 v[18:21], v[222:225], v[190:193], v[18:21]
	v_mfma_f32_16x16x32_bf16 v[14:17], v[214:217], v[198:201], v[14:17]
	v_mfma_f32_16x16x32_bf16 v[10:13], v[222:225], v[198:201], v[10:13]
	v_mfma_f32_16x16x32_bf16 v[6:9], v[214:217], v[206:209], v[6:9]
	v_mfma_f32_16x16x32_bf16 v[2:5], v[222:225], v[206:209], v[2:5]
	v_mfma_f32_16x16x32_bf16 v[30:33], v[218:221], v[186:189], v[30:33]
	v_mfma_f32_16x16x32_bf16 v[26:29], v[226:229], v[186:189], v[26:29]
	v_mfma_f32_16x16x32_bf16 v[22:25], v[218:221], v[194:197], v[22:25]
	v_mfma_f32_16x16x32_bf16 v[18:21], v[226:229], v[194:197], v[18:21]
	v_mfma_f32_16x16x32_bf16 v[14:17], v[218:221], v[202:205], v[14:17]
	v_mfma_f32_16x16x32_bf16 v[10:13], v[226:229], v[202:205], v[10:13]
	v_mfma_f32_16x16x32_bf16 v[6:9], v[218:221], v[210:213], v[6:9]
	v_mfma_f32_16x16x32_bf16 v[2:5], v[226:229], v[210:213], v[2:5]
	s_setprio 0
	s_add_i32 s17, s17, 2
	s_cmp_lt_u32 s17, 12
	s_barrier
	s_cbranch_scc1 .LBB0_89
	v_readfirstlane_b32 s42, v170
	v_readfirstlane_b32 s98, v171
	s_mov_b32 s99, 0
	s_nop 1
	s_lshl_b32 s42, s42, 4
	s_add_i32 s98, s98, s3
	s_cmpk_gt_i32 s98, 0x57f
	s_cbranch_scc1 .Lup0_noearly
	s_mul_hi_i32 s43, s98, 0x2e8ba2e9
	s_lshr_b32 s44, s43, 31
	s_ashr_i32 s43, s43, 5
	s_add_i32 s43, s43, s44
	s_mul_i32 s44, s43, 0xb0
	s_sub_i32 s44, s98, s44
	s_lshl_b32 s43, s43, 3
	s_and_b32 s45, s44, 7
	s_or_b32 s43, s45, s43
	s_ashr_i32 s44, s44, 3
	s_lshl_b32 s43, s43, 19
	s_lshl_b32 s44, s44, 19
	s_add_u32 s100, s26, s43
	s_addc_u32 s101, s27, 0
	s_add_u32 s98, s4, s44
	s_addc_u32 s99, s5, 0
.Lup0_noearly:
	ds_read_b128 v[146:149], v144
	ds_read_b128 v[152:155], v144 offset:1024
	ds_read_b128 v[156:159], v144 offset:2048
	ds_read_b128 v[160:163], v144 offset:3072
	ds_read_b128 v[164:167], v140
	ds_read_b128 v[174:177], v140 offset:1024
	ds_read_b128 v[178:181], v139
	ds_read_b128 v[182:185], v139 offset:1024
	ds_read_b128 v[186:189], v138
	ds_read_b128 v[190:193], v138 offset:1024
	ds_read_b128 v[194:197], v137
	ds_read_b128 v[198:201], v137 offset:1024
	v_lshl_add_u64 v[144:145], s[14:15], 0, v[130:131]
	v_readfirstlane_b32 s17, v151
	v_lshl_add_u64 v[144:145], v[144:145], 0, s[8:9]
	s_mov_b32 m0, s17
	v_lshl_add_u64 v[132:133], s[14:15], 0, v[132:133]
	v_readfirstlane_b32 s14, v150
	global_load_lds_dwordx4 v[144:145], off
	v_lshl_add_u64 v[132:133], v[132:133], 0, s[8:9]
	s_mov_b32 m0, s14
	s_nop 0
	global_load_lds_dwordx4 v[132:133], off
	s_waitcnt vmcnt(10)
	s_barrier
	s_waitcnt lgkmcnt(0)
	s_setprio 1
	s_waitcnt lgkmcnt(0)
	v_mfma_f32_16x16x32_bf16 v[126:129], v[146:149], v[164:167], v[126:129]
	v_mfma_f32_16x16x32_bf16 v[122:125], v[156:159], v[164:167], v[122:125]
	v_mfma_f32_16x16x32_bf16 v[110:113], v[146:149], v[186:189], v[110:113]
	v_mfma_f32_16x16x32_bf16 v[106:109], v[156:159], v[186:189], v[106:109]
	v_mfma_f32_16x16x32_bf16 v[126:129], v[152:155], v[174:177], v[126:129]
	v_mfma_f32_16x16x32_bf16 v[122:125], v[160:163], v[174:177], v[122:125]
	v_mfma_f32_16x16x32_bf16 v[118:121], v[146:149], v[178:181], v[118:121]
	v_mfma_f32_16x16x32_bf16 v[114:117], v[156:159], v[178:181], v[114:117]
	v_mfma_f32_16x16x32_bf16 v[110:113], v[152:155], v[190:193], v[110:113]
	v_mfma_f32_16x16x32_bf16 v[106:109], v[160:163], v[190:193], v[106:109]
	v_mfma_f32_16x16x32_bf16 v[102:105], v[146:149], v[194:197], v[102:105]
	v_mfma_f32_16x16x32_bf16 v[98:101], v[156:159], v[194:197], v[98:101]
	v_mfma_f32_16x16x32_bf16 v[202:205], v[152:155], v[182:185], v[118:121]
	v_mfma_f32_16x16x32_bf16 v[206:209], v[160:163], v[182:185], v[114:117]
	v_mfma_f32_16x16x32_bf16 v[210:213], v[152:155], v[198:201], v[102:105]
	v_mfma_f32_16x16x32_bf16 v[214:217], v[160:163], v[198:201], v[98:101]
	s_setprio 0
	s_barrier
; #define STAGE(P, GP, ktrel) do { const GAS char* _g = (GP) + (ktrel) * (BK * 2); \
;     __builtin_amdgcn_global_load_lds((const GAS unsigned*)(_g + so0), (unsigned*)((char*)(P) + tid_ * 16), 16, 0, 0); \
;     __builtin_amdgcn_global_load_lds((const GAS unsigned*)(_g + so1), (unsigned*)((char*)(P) + tid_ * 16 + 8192), 16, 0, 0); } while (0)
; #define WAIT_V(n) asm volatile("s_waitcnt vmcnt(" #n ")" ::: "memory")
; #define WAIT_L(n) asm volatile("s_waitcnt lgkmcnt(" #n ")" ::: "memory")
; #define BAR __builtin_amdgcn_s_barrier()
; #define LDA(dst, b, h) for (int m = 0; m < 4; ++m) for (int k = 0; k < 2; ++k) \
;     dst[m][k] = *reinterpret_cast<const bf16x8*>((char*)SA(b, h) + lds_byte(wr * 64 + m * 16 + fr, k * 32 + fq * 8))
; #define LDB(dst, b, h) for (int n = 0; n < 2; ++n) for (int k = 0; k < 2; ++k) \
;     dst[n][k] = *reinterpret_cast<const bf16x8*>((char*)SB(b, h) + lds_byte(wc * 32 + n * 16 + fr, k * 32 + fq * 8))
; #define MMA(ai, bj, At_, Bt_) do { __builtin_amdgcn_s_setprio(1); \
;     for (int m = 0; m < 4; ++m) for (int n = 0; n < 2; ++n) for (int k = 0; k < 2; ++k) \
;       acc[ai][bj][m][n] = __builtin_amdgcn_mfma_f32_16x16x32_bf16(At_[m][k], Bt_[n][k], acc[ai][bj][m][n], 0, 0, 0); \
;     __builtin_amdgcn_s_setprio(0); } while (0)
; template <int K, int LD = K>
; __device__ __forceinline__ void gemm_prefetch(const GAS bf16* A, const GAS bf16* Bt, int brow, int bcol) {
;     ...
;   STAGE(SB(0, 0), pB0, 0); STAGE(SA(0, 0), pA0, 0);
; template <int K, int LD = K>
; __device__ __forceinline__ void gemm_main(const GAS bf16* A, const GAS bf16* Bt, int brow, int bcol, f32x4 (&acc)[2][2][4][2]) {
;     ...
;     LDB(B1, 0, 1); BAR; WAIT_L(0); MMA(0, 1, At, B1); BAR;
;     LDA(At, 0, 1); WAIT_V(4); BAR; WAIT_L(0); MMA(1, 0, At, B0); MMA(1, 1, At, B1); BAR; }
;   { LDB(B0, 1, 0); LDA(At, 1, 0); WAIT_V(2); BAR; WAIT_L(0); MMA(0, 0, At, B0); BAR;
;     LDB(B1, 1, 1); WAIT_V(0); BAR; WAIT_L(0); MMA(0, 1, At, B1); BAR;
;     LDA(At, 1, 1); BAR; WAIT_L(0); MMA(1, 0, At, B0); MMA(1, 1, At, B1); BAR; }
	s_nop 1
	ds_read_b128 v[98:101], v143
	ds_read_b128 v[102:105], v143 offset:1024
	ds_read_b128 v[114:117], v143 offset:2048
	ds_read_b128 v[118:121], v143 offset:3072
	s_waitcnt vmcnt(8)
	s_barrier
	s_waitcnt lgkmcnt(0)
	s_setprio 1
	s_waitcnt lgkmcnt(0)
	v_mfma_f32_16x16x32_bf16 v[94:97], v[98:101], v[164:167], v[94:97]
	v_mfma_f32_16x16x32_bf16 v[90:93], v[114:117], v[164:167], v[90:93]
	v_mfma_f32_16x16x32_bf16 v[78:81], v[98:101], v[186:189], v[78:81]
	v_mfma_f32_16x16x32_bf16 v[74:77], v[114:117], v[186:189], v[74:77]
	v_mfma_f32_16x16x32_bf16 v[94:97], v[102:105], v[174:177], v[94:97]
	v_mfma_f32_16x16x32_bf16 v[90:93], v[118:121], v[174:177], v[90:93]
	v_mfma_f32_16x16x32_bf16 v[86:89], v[98:101], v[178:181], v[86:89]
	v_mfma_f32_16x16x32_bf16 v[82:85], v[114:117], v[178:181], v[82:85]
	v_mfma_f32_16x16x32_bf16 v[78:81], v[102:105], v[190:193], v[78:81]
	v_mfma_f32_16x16x32_bf16 v[74:77], v[118:121], v[190:193], v[74:77]
	v_mfma_f32_16x16x32_bf16 v[70:73], v[98:101], v[194:197], v[70:73]
	v_mfma_f32_16x16x32_bf16 v[66:69], v[114:117], v[194:197], v[66:69]
	v_mfma_f32_16x16x32_bf16 v[164:167], v[102:105], v[182:185], v[86:89]
	v_mfma_f32_16x16x32_bf16 v[174:177], v[118:121], v[182:185], v[82:85]
	v_mfma_f32_16x16x32_bf16 v[178:181], v[102:105], v[198:201], v[70:73]
	v_mfma_f32_16x16x32_bf16 v[182:185], v[118:121], v[198:201], v[66:69]
	s_setprio 0
	s_barrier
	s_nop 1
	ds_read_b128 v[66:69], v140 offset:16384
	ds_read_b128 v[70:73], v140 offset:17408
	ds_read_b128 v[82:85], v139 offset:16384
	ds_read_b128 v[86:89], v139 offset:17408
	ds_read_b128 v[186:189], v138 offset:16384
	ds_read_b128 v[190:193], v138 offset:17408
	ds_read_b128 v[194:197], v137 offset:16384
	ds_read_b128 v[198:201], v137 offset:17408
	s_waitcnt vmcnt(4)
	s_barrier
	s_waitcnt lgkmcnt(0)
	s_setprio 1
	s_waitcnt lgkmcnt(0)
	v_mfma_f32_16x16x32_bf16 v[62:65], v[146:149], v[66:69], v[62:65]
	v_mfma_f32_16x16x32_bf16 v[58:61], v[156:159], v[66:69], v[58:61]
	v_mfma_f32_16x16x32_bf16 v[46:49], v[146:149], v[186:189], v[46:49]
	v_mfma_f32_16x16x32_bf16 v[38:41], v[146:149], v[194:197], v[38:41]
	v_mfma_f32_16x16x32_bf16 v[62:65], v[152:155], v[70:73], v[62:65]
	v_mfma_f32_16x16x32_bf16 v[58:61], v[160:163], v[70:73], v[58:61]
	v_mfma_f32_16x16x32_bf16 v[54:57], v[146:149], v[82:85], v[54:57]
	v_mfma_f32_16x16x32_bf16 v[50:53], v[156:159], v[82:85], v[50:53]
	v_mfma_f32_16x16x32_bf16 v[46:49], v[152:155], v[190:193], v[46:49]
	v_mfma_f32_16x16x32_bf16 v[42:45], v[156:159], v[186:189], v[42:45]
	v_mfma_f32_16x16x32_bf16 v[38:41], v[152:155], v[198:201], v[38:41]
	v_mfma_f32_16x16x32_bf16 v[34:37], v[156:159], v[194:197], v[34:37]
	v_mfma_f32_16x16x32_bf16 v[218:221], v[152:155], v[86:89], v[54:57]
	v_mfma_f32_16x16x32_bf16 v[222:225], v[160:163], v[86:89], v[50:53]
	v_mfma_f32_16x16x32_bf16 v[226:229], v[160:163], v[190:193], v[42:45]
	v_mfma_f32_16x16x32_bf16 v[144:147], v[160:163], v[198:201], v[34:37]
	s_setprio 0
	s_setprio 1
	v_mfma_f32_16x16x32_bf16 v[30:33], v[98:101], v[66:69], v[30:33]
	v_mfma_f32_16x16x32_bf16 v[26:29], v[114:117], v[66:69], v[26:29]
	v_mfma_f32_16x16x32_bf16 v[14:17], v[98:101], v[186:189], v[14:17]
	v_mfma_f32_16x16x32_bf16 v[6:9], v[98:101], v[194:197], v[6:9]
	v_mfma_f32_16x16x32_bf16 v[30:33], v[102:105], v[70:73], v[30:33]
	v_mfma_f32_16x16x32_bf16 v[26:29], v[118:121], v[70:73], v[26:29]
	v_mfma_f32_16x16x32_bf16 v[22:25], v[98:101], v[82:85], v[22:25]
	v_mfma_f32_16x16x32_bf16 v[18:21], v[114:117], v[82:85], v[18:21]
	v_mfma_f32_16x16x32_bf16 v[14:17], v[102:105], v[190:193], v[14:17]
	v_mfma_f32_16x16x32_bf16 v[10:13], v[114:117], v[186:189], v[10:13]
	v_mfma_f32_16x16x32_bf16 v[6:9], v[102:105], v[198:201], v[6:9]
	v_mfma_f32_16x16x32_bf16 v[2:5], v[114:117], v[194:197], v[2:5]
	v_mfma_f32_16x16x32_bf16 v[148:151], v[102:105], v[86:89], v[22:25]
	v_mfma_f32_16x16x32_bf16 v[152:155], v[118:121], v[86:89], v[18:21]
	v_mfma_f32_16x16x32_bf16 v[156:159], v[118:121], v[190:193], v[10:13]
	v_mfma_f32_16x16x32_bf16 v[160:163], v[118:121], v[198:201], v[2:5]
	s_setprio 0
	s_barrier
	s_nop 1
	ds_read_b128 v[2:5], v142
	ds_read_b128 v[10:13], v142 offset:1024
	ds_read_b128 v[186:189], v142 offset:2048
	ds_read_b128 v[190:193], v142 offset:3072
	ds_read_b128 v[18:21], v140 offset:32768
	ds_read_b128 v[22:25], v140 offset:33792
	ds_read_b128 v[34:37], v139 offset:32768
	ds_read_b128 v[42:45], v139 offset:33792
	ds_read_b128 v[50:53], v138 offset:32768
	ds_read_b128 v[54:57], v138 offset:33792
	ds_read_b128 v[194:197], v137 offset:32768
	ds_read_b128 v[198:201], v137 offset:33792
	s_waitcnt vmcnt(2)
	s_barrier
	s_waitcnt lgkmcnt(0)
	s_setprio 1
	s_waitcnt lgkmcnt(0)
	v_mfma_f32_16x16x32_bf16 v[66:69], v[2:5], v[18:21], v[126:129]
	v_mfma_f32_16x16x32_bf16 v[118:121], v[10:13], v[22:25], v[66:69]
	v_mfma_f32_16x16x32_bf16 v[66:69], v[186:189], v[18:21], v[122:125]
	v_mfma_f32_16x16x32_bf16 v[114:117], v[190:193], v[22:25], v[66:69]
	v_mfma_f32_16x16x32_bf16 v[66:69], v[2:5], v[34:37], v[202:205]
	v_mfma_f32_16x16x32_bf16 v[102:105], v[10:13], v[42:45], v[66:69]
	v_mfma_f32_16x16x32_bf16 v[66:69], v[186:189], v[34:37], v[206:209]
	v_mfma_f32_16x16x32_bf16 v[98:101], v[190:193], v[42:45], v[66:69]
	v_mfma_f32_16x16x32_bf16 v[66:69], v[2:5], v[50:53], v[110:113]
	v_mfma_f32_16x16x32_bf16 v[86:89], v[10:13], v[54:57], v[66:69]
	v_mfma_f32_16x16x32_bf16 v[66:69], v[186:189], v[50:53], v[106:109]
	v_mfma_f32_16x16x32_bf16 v[82:85], v[190:193], v[54:57], v[66:69]
	v_mfma_f32_16x16x32_bf16 v[66:69], v[2:5], v[194:197], v[210:213]
	v_mfma_f32_16x16x32_bf16 v[70:73], v[10:13], v[198:201], v[66:69]
	v_mfma_f32_16x16x32_bf16 v[66:69], v[186:189], v[194:197], v[214:217]
	v_mfma_f32_16x16x32_bf16 v[66:69], v[190:193], v[198:201], v[66:69]
	s_setprio 0
	s_barrier
	ds_read_b128 v[202:205], v141
	ds_read_b128 v[206:209], v141 offset:1024
	ds_read_b128 v[210:213], v141 offset:2048
	ds_read_b128 v[214:217], v141 offset:3072
	s_waitcnt vmcnt(0)
	s_cmp_eq_u32 s99, 0
	s_cbranch_scc1 .Lup0_early2_skip
	s_add_i32 s43, s42, 0x10100
	s_mov_b32 m0, s43
	s_nop 0
	global_load_lds_dwordx4 v130, s[98:99]
	s_add_u32 s98, s98, 0x20000
	s_addc_u32 s99, s99, 0
	s_add_i32 s43, s42, 0x12100
	s_mov_b32 m0, s43
	s_nop 0
	global_load_lds_dwordx4 v130, s[98:99]
	s_add_i32 s43, s42, 0x100
	s_mov_b32 m0, s43
	s_nop 0
	global_load_lds_dwordx4 v130, s[100:101]
	s_add_u32 s100, s100, 0x20000
	s_addc_u32 s101, s101, 0
	s_add_i32 s43, s42, 0x2100
	s_mov_b32 m0, s43
	s_nop 0
	global_load_lds_dwordx4 v130, s[100:101]

; #define STAGE(P, GP, ktrel) do { const GAS char* _g = (GP) + (ktrel) * (BK * 2); \
;     __builtin_amdgcn_global_load_lds((const GAS unsigned*)(_g + so0), (unsigned*)((char*)(P) + tid_ * 16), 16, 0, 0); \
;     __builtin_amdgcn_global_load_lds((const GAS unsigned*)(_g + so1), (unsigned*)((char*)(P) + tid_ * 16 + 8192), 16, 0, 0); } while (0)
; #define WAIT_V(n) asm volatile("s_waitcnt vmcnt(" #n ")" ::: "memory")
; #define WAIT_L(n) asm volatile("s_waitcnt lgkmcnt(" #n ")" ::: "memory")
; #define BAR __builtin_amdgcn_s_barrier()
; #define SCHED __builtin_amdgcn_sched_barrier(0)
; #define LDA(dst, b, h) for (int m = 0; m < 4; ++m) for (int k = 0; k < 2; ++k) \
;     dst[m][k] = *reinterpret_cast<const bf16x8*>((char*)SA(b, h) + lds_byte(wr * 64 + m * 16 + fr, k * 32 + fq * 8))
; #define LDB(dst, b, h) for (int n = 0; n < 2; ++n) for (int k = 0; k < 2; ++k) \
;     dst[n][k] = *reinterpret_cast<const bf16x8*>((char*)SB(b, h) + lds_byte(wc * 32 + n * 16 + fr, k * 32 + fq * 8))
; #define MMA(ai, bj, At_, Bt_) do { __builtin_amdgcn_s_setprio(1); \
;     for (int m = 0; m < 4; ++m) for (int n = 0; n < 2; ++n) for (int k = 0; k < 2; ++k) \
;       acc[ai][bj][m][n] = __builtin_amdgcn_mfma_f32_16x16x32_bf16(At_[m][k], Bt_[n][k], acc[ai][bj][m][n], 0, 0, 0); \
;     __builtin_amdgcn_s_setprio(0); } while (0)
; template <int K, int LD = K>
; __device__ __forceinline__ void gemm_main(const GAS bf16* A, const GAS bf16* Bt, int brow, int bcol, f32x4 (&acc)[2][2][4][2]) {
;     ...
;   for (int t = 0; t < nt - 2; t += 2) {
;     LDB(B0, 0, 0); SCHED; LDA(At, 0, 0); STAGE(SA(1, 1), pA1, 1);
;     WAIT_L(8); BAR; WAIT_L(0); MMA(0, 0, At, B0); BAR; SCHED;
;     LDB(B1, 0, 1); STAGE(SB(0, 0), pB0, 2);
;     BAR; WAIT_L(0); MMA(0, 1, At, B1); BAR;
;     LDA(At, 0, 1); STAGE(SA(0, 0), pA0, 2);
;     BAR; WAIT_L(0); MMA(1, 0, At, B0); BAR; SCHED;
;     STAGE(SB(0, 1), pB1, 2);
;     WAIT_V(6); BAR; MMA(1, 1, At, B1); BAR;
;     LDB(B0, 1, 0); SCHED; LDA(At, 1, 0); STAGE(SA(0, 1), pA1, 2);
;     WAIT_L(8); BAR; WAIT_L(0); MMA(0, 0, At, B0); BAR; SCHED;
;     LDB(B1, 1, 1); STAGE(SB(1, 0), pB0, 3);
;     BAR; WAIT_L(0); MMA(0, 1, At, B1); BAR;
.LBB0_884:
	ds_read_b128 v[160:163], v145
	ds_read_b128 v[164:167], v145 offset:1024
	ds_read_b128 v[174:177], v145 offset:2048
	ds_read_b128 v[178:181], v145 offset:3072
	v_lshl_add_u64 v[168:169], s[12:13], 0, v[130:131]
	v_readfirstlane_b32 s22, v144
	v_lshl_add_u64 v[214:215], v[168:169], 0, s[6:7]
	s_mov_b32 m0, s22
	v_lshl_add_u64 v[230:231], s[12:13], 0, v[132:133]
	v_readfirstlane_b32 s22, v143
	ds_read_b128 v[182:185], v139
	ds_read_b128 v[186:189], v139 offset:1024
	ds_read_b128 v[190:193], v138
	ds_read_b128 v[194:197], v138 offset:1024
	ds_read_b128 v[198:201], v137
	ds_read_b128 v[202:205], v137 offset:1024
	ds_read_b128 v[206:209], v136
	ds_read_b128 v[210:213], v136 offset:1024
	global_load_lds_dwordx4 v[214:215], off
	v_lshl_add_u64 v[214:215], v[230:231], 0, s[6:7]
	s_mov_b32 m0, s22
	s_nop 0
	global_load_lds_dwordx4 v[214:215], off
	s_waitcnt lgkmcnt(8)
	s_waitcnt vmcnt(10)
	s_barrier
	s_waitcnt lgkmcnt(0)
	s_setprio 1
	s_waitcnt lgkmcnt(0)
	v_mfma_f32_16x16x32_bf16 v[126:129], v[160:163], v[182:185], v[126:129]
	v_mfma_f32_16x16x32_bf16 v[122:125], v[174:177], v[182:185], v[122:125]
	v_mfma_f32_16x16x32_bf16 v[118:121], v[160:163], v[190:193], v[118:121]
	v_mfma_f32_16x16x32_bf16 v[114:117], v[174:177], v[190:193], v[114:117]
	v_mfma_f32_16x16x32_bf16 v[110:113], v[160:163], v[198:201], v[110:113]
	v_mfma_f32_16x16x32_bf16 v[106:109], v[174:177], v[198:201], v[106:109]
	v_mfma_f32_16x16x32_bf16 v[102:105], v[160:163], v[206:209], v[102:105]
	v_mfma_f32_16x16x32_bf16 v[98:101], v[174:177], v[206:209], v[98:101]
	v_mfma_f32_16x16x32_bf16 v[126:129], v[164:167], v[186:189], v[126:129]
	v_mfma_f32_16x16x32_bf16 v[122:125], v[178:181], v[186:189], v[122:125]
	v_mfma_f32_16x16x32_bf16 v[118:121], v[164:167], v[194:197], v[118:121]
	v_mfma_f32_16x16x32_bf16 v[114:117], v[178:181], v[194:197], v[114:117]
	v_mfma_f32_16x16x32_bf16 v[110:113], v[164:167], v[202:205], v[110:113]
	v_mfma_f32_16x16x32_bf16 v[106:109], v[178:181], v[202:205], v[106:109]
	v_mfma_f32_16x16x32_bf16 v[102:105], v[164:167], v[210:213], v[102:105]
	v_mfma_f32_16x16x32_bf16 v[98:101], v[178:181], v[210:213], v[98:101]
	s_setprio 0
	s_barrier
	v_lshl_add_u64 v[232:233], s[20:21], 0, v[130:131]
	v_readfirstlane_b32 s22, v152
	v_lshl_add_u64 v[234:235], v[232:233], 0, s[8:9]
	s_mov_b32 m0, s22
	ds_read_b128 v[214:217], v142
	ds_read_b128 v[218:221], v142 offset:1024
	ds_read_b128 v[222:225], v142 offset:2048
	ds_read_b128 v[226:229], v142 offset:3072
	global_load_lds_dwordx4 v[234:235], off
	v_lshl_add_u64 v[234:235], s[20:21], 0, v[132:133]
	v_readfirstlane_b32 s22, v153
	v_lshl_add_u64 v[236:237], v[234:235], 0, s[8:9]
	s_mov_b32 m0, s22
	s_add_u32 s20, s20, 0x100
	global_load_lds_dwordx4 v[236:237], off
	s_waitcnt vmcnt(10)
	s_barrier
	s_waitcnt lgkmcnt(0)
	s_addc_u32 s21, s21, 0
	s_setprio 1
	s_waitcnt lgkmcnt(0)
	v_mfma_f32_16x16x32_bf16 v[94:97], v[214:217], v[182:185], v[94:97]
	v_mfma_f32_16x16x32_bf16 v[90:93], v[222:225], v[182:185], v[90:93]
	v_mfma_f32_16x16x32_bf16 v[86:89], v[214:217], v[190:193], v[86:89]
	v_mfma_f32_16x16x32_bf16 v[82:85], v[222:225], v[190:193], v[82:85]
	v_mfma_f32_16x16x32_bf16 v[78:81], v[214:217], v[198:201], v[78:81]
	v_mfma_f32_16x16x32_bf16 v[74:77], v[222:225], v[198:201], v[74:77]
	v_mfma_f32_16x16x32_bf16 v[70:73], v[214:217], v[206:209], v[70:73]
	v_mfma_f32_16x16x32_bf16 v[66:69], v[222:225], v[206:209], v[66:69]
	v_mfma_f32_16x16x32_bf16 v[94:97], v[218:221], v[186:189], v[94:97]
	v_mfma_f32_16x16x32_bf16 v[90:93], v[226:229], v[186:189], v[90:93]
	v_mfma_f32_16x16x32_bf16 v[86:89], v[218:221], v[194:197], v[86:89]
	v_mfma_f32_16x16x32_bf16 v[82:85], v[226:229], v[194:197], v[82:85]
	v_mfma_f32_16x16x32_bf16 v[78:81], v[218:221], v[202:205], v[78:81]
	v_mfma_f32_16x16x32_bf16 v[74:77], v[226:229], v[202:205], v[74:77]
	v_mfma_f32_16x16x32_bf16 v[70:73], v[218:221], v[210:213], v[70:73]
	v_mfma_f32_16x16x32_bf16 v[66:69], v[226:229], v[210:213], v[66:69]
	s_setprio 0
	v_lshl_add_u64 v[236:237], s[18:19], 0, v[130:131]
	v_readfirstlane_b32 s22, v146
	v_lshl_add_u64 v[238:239], v[236:237], 0, s[8:9]
	s_mov_b32 m0, s22
	s_barrier
	ds_read_b128 v[182:185], v139 offset:16384
	ds_read_b128 v[186:189], v139 offset:17408
	ds_read_b128 v[190:193], v138 offset:16384
	ds_read_b128 v[194:197], v138 offset:17408
	ds_read_b128 v[198:201], v137 offset:16384
	ds_read_b128 v[202:205], v137 offset:17408
	ds_read_b128 v[206:209], v136 offset:16384
	ds_read_b128 v[210:213], v136 offset:17408
	global_load_lds_dwordx4 v[238:239], off
	v_lshl_add_u64 v[238:239], s[18:19], 0, v[132:133]
	v_readfirstlane_b32 s22, v147
	v_lshl_add_u64 v[240:241], v[238:239], 0, s[8:9]
	s_mov_b32 m0, s22
	s_add_u32 s18, s18, 0x100
	global_load_lds_dwordx4 v[240:241], off
	s_barrier
	s_waitcnt lgkmcnt(0)
	s_addc_u32 s19, s19, 0
	s_setprio 1
	s_waitcnt lgkmcnt(0)
	v_mfma_f32_16x16x32_bf16 v[62:65], v[160:163], v[182:185], v[62:65]
	v_mfma_f32_16x16x32_bf16 v[58:61], v[174:177], v[182:185], v[58:61]
	v_mfma_f32_16x16x32_bf16 v[54:57], v[160:163], v[190:193], v[54:57]
	v_mfma_f32_16x16x32_bf16 v[50:53], v[174:177], v[190:193], v[50:53]
	v_mfma_f32_16x16x32_bf16 v[46:49], v[160:163], v[198:201], v[46:49]
	v_mfma_f32_16x16x32_bf16 v[42:45], v[174:177], v[198:201], v[42:45]
	v_mfma_f32_16x16x32_bf16 v[38:41], v[160:163], v[206:209], v[38:41]
	v_mfma_f32_16x16x32_bf16 v[34:37], v[174:177], v[206:209], v[34:37]
	v_mfma_f32_16x16x32_bf16 v[62:65], v[164:167], v[186:189], v[62:65]
	v_mfma_f32_16x16x32_bf16 v[58:61], v[178:181], v[186:189], v[58:61]
	v_mfma_f32_16x16x32_bf16 v[54:57], v[164:167], v[194:197], v[54:57]
	v_mfma_f32_16x16x32_bf16 v[50:53], v[178:181], v[194:197], v[50:53]
	v_mfma_f32_16x16x32_bf16 v[46:49], v[164:167], v[202:205], v[46:49]
	v_mfma_f32_16x16x32_bf16 v[42:45], v[178:181], v[202:205], v[42:45]
	v_mfma_f32_16x16x32_bf16 v[38:41], v[164:167], v[210:213], v[38:41]
	v_mfma_f32_16x16x32_bf16 v[34:37], v[178:181], v[210:213], v[34:37]
	s_setprio 0
	s_barrier
; #define STAGE(P, GP, ktrel) do { const GAS char* _g = (GP) + (ktrel) * (BK * 2); \
;     __builtin_amdgcn_global_load_lds((const GAS unsigned*)(_g + so0), (unsigned*)((char*)(P) + tid_ * 16), 16, 0, 0); \
;     __builtin_amdgcn_global_load_lds((const GAS unsigned*)(_g + so1), (unsigned*)((char*)(P) + tid_ * 16 + 8192), 16, 0, 0); } while (0)
; #define WAIT_V(n) asm volatile("s_waitcnt vmcnt(" #n ")" ::: "memory")
; #define WAIT_L(n) asm volatile("s_waitcnt lgkmcnt(" #n ")" ::: "memory")
; #define BAR __builtin_amdgcn_s_barrier()
; #define SCHED __builtin_amdgcn_sched_barrier(0)
; #define LDA(dst, b, h) for (int m = 0; m < 4; ++m) for (int k = 0; k < 2; ++k) \
;     dst[m][k] = *reinterpret_cast<const bf16x8*>((char*)SA(b, h) + lds_byte(wr * 64 + m * 16 + fr, k * 32 + fq * 8))
; #define LDB(dst, b, h) for (int n = 0; n < 2; ++n) for (int k = 0; k < 2; ++k) \
;     dst[n][k] = *reinterpret_cast<const bf16x8*>((char*)SB(b, h) + lds_byte(wc * 32 + n * 16 + fr, k * 32 + fq * 8))
; #define MMA(ai, bj, At_, Bt_) do { __builtin_amdgcn_s_setprio(1); \
;     for (int m = 0; m < 4; ++m) for (int n = 0; n < 2; ++n) for (int k = 0; k < 2; ++k) \
;       acc[ai][bj][m][n] = __builtin_amdgcn_mfma_f32_16x16x32_bf16(At_[m][k], Bt_[n][k], acc[ai][bj][m][n], 0, 0, 0); \
;     __builtin_amdgcn_s_setprio(0); } while (0)
; template <int K, int LD = K>
; __device__ __forceinline__ void gemm_main(const GAS bf16* A, const GAS bf16* Bt, int brow, int bcol, f32x4 (&acc)[2][2][4][2]) {
;     ...
;     STAGE(SB(0, 1), pB1, 2);
;     WAIT_V(6); BAR; MMA(1, 1, At, B1); BAR;
;     LDB(B0, 1, 0); SCHED; LDA(At, 1, 0); STAGE(SA(0, 1), pA1, 2);
;     WAIT_L(8); BAR; WAIT_L(0); MMA(0, 0, At, B0); BAR; SCHED;
;     LDB(B1, 1, 1); STAGE(SB(1, 0), pB0, 3);
;     BAR; WAIT_L(0); MMA(0, 1, At, B1); BAR;
;     LDA(At, 1, 1); STAGE(SA(1, 0), pA0, 3);
;     BAR; WAIT_L(0); MMA(1, 0, At, B0); BAR; SCHED;
	v_lshl_add_u64 v[240:241], s[16:17], 0, v[130:131]
	v_readfirstlane_b32 s22, v154
	v_lshl_add_u64 v[160:161], v[240:241], 0, s[8:9]
	s_mov_b32 m0, s22
	v_lshl_add_u64 v[242:243], s[16:17], 0, v[132:133]
	v_readfirstlane_b32 s22, v155
	global_load_lds_dwordx4 v[160:161], off
	v_lshl_add_u64 v[160:161], v[242:243], 0, s[8:9]
	s_mov_b32 m0, s22
	s_add_u32 s16, s16, 0x100
	global_load_lds_dwordx4 v[160:161], off
	s_waitcnt vmcnt(10)
	s_addc_u32 s17, s17, 0
	s_barrier
	s_setprio 1
	v_mfma_f32_16x16x32_bf16 v[30:33], v[214:217], v[182:185], v[30:33]
	v_mfma_f32_16x16x32_bf16 v[26:29], v[222:225], v[182:185], v[26:29]
	v_mfma_f32_16x16x32_bf16 v[22:25], v[214:217], v[190:193], v[22:25]
	v_mfma_f32_16x16x32_bf16 v[18:21], v[222:225], v[190:193], v[18:21]
	v_mfma_f32_16x16x32_bf16 v[14:17], v[214:217], v[198:201], v[14:17]
	v_mfma_f32_16x16x32_bf16 v[10:13], v[222:225], v[198:201], v[10:13]
	v_mfma_f32_16x16x32_bf16 v[6:9], v[214:217], v[206:209], v[6:9]
	v_mfma_f32_16x16x32_bf16 v[2:5], v[222:225], v[206:209], v[2:5]
	v_mfma_f32_16x16x32_bf16 v[30:33], v[218:221], v[186:189], v[30:33]
	v_mfma_f32_16x16x32_bf16 v[26:29], v[226:229], v[186:189], v[26:29]
	v_mfma_f32_16x16x32_bf16 v[22:25], v[218:221], v[194:197], v[22:25]
	v_mfma_f32_16x16x32_bf16 v[18:21], v[226:229], v[194:197], v[18:21]
	v_mfma_f32_16x16x32_bf16 v[14:17], v[218:221], v[202:205], v[14:17]
	v_mfma_f32_16x16x32_bf16 v[10:13], v[226:229], v[202:205], v[10:13]
	v_mfma_f32_16x16x32_bf16 v[6:9], v[218:221], v[210:213], v[6:9]
	v_mfma_f32_16x16x32_bf16 v[2:5], v[226:229], v[210:213], v[2:5]
	s_setprio 0
	s_barrier
	ds_read_b128 v[160:163], v141
	ds_read_b128 v[164:167], v141 offset:1024
	ds_read_b128 v[174:177], v141 offset:2048
	ds_read_b128 v[178:181], v141 offset:3072
	v_readfirstlane_b32 s22, v148
	v_lshl_add_u64 v[168:169], v[168:169], 0, s[8:9]
	s_mov_b32 m0, s22
	v_readfirstlane_b32 s22, v149
	ds_read_b128 v[182:185], v139 offset:32768
	ds_read_b128 v[186:189], v139 offset:33792
	ds_read_b128 v[190:193], v138 offset:32768
	ds_read_b128 v[194:197], v138 offset:33792
	ds_read_b128 v[198:201], v137 offset:32768
	ds_read_b128 v[202:205], v137 offset:33792
	ds_read_b128 v[206:209], v136 offset:32768
	ds_read_b128 v[210:213], v136 offset:33792
	global_load_lds_dwordx4 v[168:169], off
	v_lshl_add_u64 v[168:169], v[230:231], 0, s[8:9]
	s_mov_b32 m0, s22
	s_add_u32 s12, s12, 0x100
	global_load_lds_dwordx4 v[168:169], off
	s_waitcnt lgkmcnt(8)
	s_waitcnt vmcnt(10)
	s_barrier
	s_waitcnt lgkmcnt(0)
	s_addc_u32 s13, s13, 0
	s_setprio 1
	s_waitcnt lgkmcnt(0)
	v_mfma_f32_16x16x32_bf16 v[126:129], v[160:163], v[182:185], v[126:129]
	v_mfma_f32_16x16x32_bf16 v[122:125], v[174:177], v[182:185], v[122:125]
	v_mfma_f32_16x16x32_bf16 v[118:121], v[160:163], v[190:193], v[118:121]
	v_mfma_f32_16x16x32_bf16 v[114:117], v[174:177], v[190:193], v[114:117]
	v_mfma_f32_16x16x32_bf16 v[110:113], v[160:163], v[198:201], v[110:113]
	v_mfma_f32_16x16x32_bf16 v[106:109], v[174:177], v[198:201], v[106:109]
	v_mfma_f32_16x16x32_bf16 v[102:105], v[160:163], v[206:209], v[102:105]
	v_mfma_f32_16x16x32_bf16 v[98:101], v[174:177], v[206:209], v[98:101]
	v_mfma_f32_16x16x32_bf16 v[126:129], v[164:167], v[186:189], v[126:129]
	v_mfma_f32_16x16x32_bf16 v[122:125], v[178:181], v[186:189], v[122:125]
	v_mfma_f32_16x16x32_bf16 v[118:121], v[164:167], v[194:197], v[118:121]
	v_mfma_f32_16x16x32_bf16 v[114:117], v[178:181], v[194:197], v[114:117]
	v_mfma_f32_16x16x32_bf16 v[110:113], v[164:167], v[202:205], v[110:113]
	v_mfma_f32_16x16x32_bf16 v[106:109], v[178:181], v[202:205], v[106:109]
	v_mfma_f32_16x16x32_bf16 v[102:105], v[164:167], v[210:213], v[102:105]
	v_mfma_f32_16x16x32_bf16 v[98:101], v[178:181], v[210:213], v[98:101]
	s_setprio 0
	s_barrier
	v_readfirstlane_b32 s22, v156
	v_lshl_add_u64 v[168:169], v[232:233], 0, s[10:11]
	s_mov_b32 m0, s22
	v_readfirstlane_b32 s22, v157
	ds_read_b128 v[214:217], v140
	ds_read_b128 v[218:221], v140 offset:1024
	ds_read_b128 v[222:225], v140 offset:2048
	ds_read_b128 v[226:229], v140 offset:3072
	global_load_lds_dwordx4 v[168:169], off
	v_lshl_add_u64 v[168:169], v[234:235], 0, s[10:11]
	s_mov_b32 m0, s22
	s_nop 0
	global_load_lds_dwordx4 v[168:169], off
	s_waitcnt vmcnt(10)
	s_barrier
	s_waitcnt lgkmcnt(0)
	s_setprio 1
	s_waitcnt lgkmcnt(0)
	v_mfma_f32_16x16x32_bf16 v[94:97], v[214:217], v[182:185], v[94:97]
	v_mfma_f32_16x16x32_bf16 v[90:93], v[222:225], v[182:185], v[90:93]
	v_mfma_f32_16x16x32_bf16 v[86:89], v[214:217], v[190:193], v[86:89]
	v_mfma_f32_16x16x32_bf16 v[82:85], v[222:225], v[190:193], v[82:85]
	v_mfma_f32_16x16x32_bf16 v[78:81], v[214:217], v[198:201], v[78:81]
	v_mfma_f32_16x16x32_bf16 v[74:77], v[222:225], v[198:201], v[74:77]
	v_mfma_f32_16x16x32_bf16 v[70:73], v[214:217], v[206:209], v[70:73]
	v_mfma_f32_16x16x32_bf16 v[66:69], v[222:225], v[206:209], v[66:69]
	v_mfma_f32_16x16x32_bf16 v[94:97], v[218:221], v[186:189], v[94:97]
	v_mfma_f32_16x16x32_bf16 v[90:93], v[226:229], v[186:189], v[90:93]
	v_mfma_f32_16x16x32_bf16 v[86:89], v[218:221], v[194:197], v[86:89]
	v_mfma_f32_16x16x32_bf16 v[82:85], v[226:229], v[194:197], v[82:85]
	v_mfma_f32_16x16x32_bf16 v[78:81], v[218:221], v[202:205], v[78:81]
	v_mfma_f32_16x16x32_bf16 v[74:77], v[226:229], v[202:205], v[74:77]
	v_mfma_f32_16x16x32_bf16 v[70:73], v[218:221], v[210:213], v[70:73]
	v_mfma_f32_16x16x32_bf16 v[66:69], v[226:229], v[210:213], v[66:69]
	s_setprio 0
	v_readfirstlane_b32 s22, v150
	v_lshl_add_u64 v[168:169], v[236:237], 0, s[10:11]
	s_mov_b32 m0, s22
	v_readfirstlane_b32 s22, v151
	s_barrier
; #define STAGE(P, GP, ktrel) do { const GAS char* _g = (GP) + (ktrel) * (BK * 2); \
;     __builtin_amdgcn_global_load_lds((const GAS unsigned*)(_g + so0), (unsigned*)((char*)(P) + tid_ * 16), 16, 0, 0); \
;     __builtin_amdgcn_global_load_lds((const GAS unsigned*)(_g + so1), (unsigned*)((char*)(P) + tid_ * 16 + 8192), 16, 0, 0); } while (0)
; #define WAIT_V(n) asm volatile("s_waitcnt vmcnt(" #n ")" ::: "memory")
; #define WAIT_L(n) asm volatile("s_waitcnt lgkmcnt(" #n ")" ::: "memory")
; #define BAR __builtin_amdgcn_s_barrier()
; #define SCHED __builtin_amdgcn_sched_barrier(0)
; #define LDA(dst, b, h) for (int m = 0; m < 4; ++m) for (int k = 0; k < 2; ++k) \
;     dst[m][k] = *reinterpret_cast<const bf16x8*>((char*)SA(b, h) + lds_byte(wr * 64 + m * 16 + fr, k * 32 + fq * 8))
; #define LDB(dst, b, h) for (int n = 0; n < 2; ++n) for (int k = 0; k < 2; ++k) \
;     dst[n][k] = *reinterpret_cast<const bf16x8*>((char*)SB(b, h) + lds_byte(wc * 32 + n * 16 + fr, k * 32 + fq * 8))
; #define MMA(ai, bj, At_, Bt_) do { __builtin_amdgcn_s_setprio(1); \
;     for (int m = 0; m < 4; ++m) for (int n = 0; n < 2; ++n) for (int k = 0; k < 2; ++k) \
;       acc[ai][bj][m][n] = __builtin_amdgcn_mfma_f32_16x16x32_bf16(At_[m][k], Bt_[n][k], acc[ai][bj][m][n], 0, 0, 0); \
;     __builtin_amdgcn_s_setprio(0); } while (0)
; __device__ __forceinline__ int ugrid() { return __builtin_amdgcn_readfirstlane((int)gridDim.x); }
; template <int K, int LD = K>
; __device__ __forceinline__ void gemm_main(const GAS bf16* A, const GAS bf16* Bt, int brow, int bcol, f32x4 (&acc)[2][2][4][2]) {
;     ...
;     LDA(At, 1, 1); STAGE(SA(1, 0), pA0, 3);
;     BAR; WAIT_L(0); MMA(1, 0, At, B0); BAR; SCHED;
;     STAGE(SB(1, 1), pB1, 3);
;     WAIT_V(6); BAR; MMA(1, 1, At, B1); BAR;
;     pA0 += 4 * BK; pA1 += 4 * BK; pB0 += 4 * BK; pB1 += 4 * BK;
;     asm volatile("" : "+s"(pA0), "+s"(pA1), "+s"(pB0), "+s"(pB1));
;   }
;   { LDB(B0, 0, 0); LDA(At, 0, 0); STAGE(SA(1, 1), pA1, 1);
;     BAR; WAIT_L(0); MMA(0, 0, At, B0); BAR;
; __device__ __forceinline__ void phase_up(int pass) {
;     ...
;     L += ugrid();
;     if (L < NT_) { tile_coords(L, nN, pm, pn); gemm_prefetch<DM>(A, Wgu, pm * 256, pn * 256); load_rr(ssq, pm * 256, par ^ 1); }
	ds_read_b128 v[182:185], v139 offset:49152
	ds_read_b128 v[186:189], v139 offset:50176
	ds_read_b128 v[190:193], v138 offset:49152
	ds_read_b128 v[194:197], v138 offset:50176
	ds_read_b128 v[198:201], v137 offset:49152
	ds_read_b128 v[202:205], v137 offset:50176
	ds_read_b128 v[206:209], v136 offset:49152
	ds_read_b128 v[210:213], v136 offset:50176
	global_load_lds_dwordx4 v[168:169], off
	v_lshl_add_u64 v[168:169], v[238:239], 0, s[10:11]
	s_mov_b32 m0, s22
	s_nop 0
	global_load_lds_dwordx4 v[168:169], off
	s_barrier
	s_waitcnt lgkmcnt(0)
	s_setprio 1
	s_waitcnt lgkmcnt(0)
	v_mfma_f32_16x16x32_bf16 v[62:65], v[160:163], v[182:185], v[62:65]
	v_mfma_f32_16x16x32_bf16 v[58:61], v[174:177], v[182:185], v[58:61]
	v_mfma_f32_16x16x32_bf16 v[54:57], v[160:163], v[190:193], v[54:57]
	v_mfma_f32_16x16x32_bf16 v[50:53], v[174:177], v[190:193], v[50:53]
	v_mfma_f32_16x16x32_bf16 v[46:49], v[160:163], v[198:201], v[46:49]
	v_mfma_f32_16x16x32_bf16 v[42:45], v[174:177], v[198:201], v[42:45]
	v_mfma_f32_16x16x32_bf16 v[38:41], v[160:163], v[206:209], v[38:41]
	v_mfma_f32_16x16x32_bf16 v[34:37], v[174:177], v[206:209], v[34:37]
	v_mfma_f32_16x16x32_bf16 v[62:65], v[164:167], v[186:189], v[62:65]
	v_mfma_f32_16x16x32_bf16 v[58:61], v[178:181], v[186:189], v[58:61]
	v_mfma_f32_16x16x32_bf16 v[54:57], v[164:167], v[194:197], v[54:57]
	v_mfma_f32_16x16x32_bf16 v[50:53], v[178:181], v[194:197], v[50:53]
	v_mfma_f32_16x16x32_bf16 v[46:49], v[164:167], v[202:205], v[46:49]
	v_mfma_f32_16x16x32_bf16 v[42:45], v[178:181], v[202:205], v[42:45]
	v_mfma_f32_16x16x32_bf16 v[38:41], v[164:167], v[210:213], v[38:41]
	v_mfma_f32_16x16x32_bf16 v[34:37], v[178:181], v[210:213], v[34:37]
	s_setprio 0
	s_barrier
	v_readfirstlane_b32 s22, v158
	v_lshl_add_u64 v[160:161], v[240:241], 0, s[10:11]
	s_mov_b32 m0, s22
	v_readfirstlane_b32 s22, v159
	global_load_lds_dwordx4 v[160:161], off
	v_lshl_add_u64 v[160:161], v[242:243], 0, s[10:11]
	s_mov_b32 m0, s22
	s_nop 0
	global_load_lds_dwordx4 v[160:161], off
	s_waitcnt vmcnt(10)
	s_barrier
	s_setprio 1
	v_mfma_f32_16x16x32_bf16 v[30:33], v[214:217], v[182:185], v[30:33]
	v_mfma_f32_16x16x32_bf16 v[26:29], v[222:225], v[182:185], v[26:29]
	v_mfma_f32_16x16x32_bf16 v[22:25], v[214:217], v[190:193], v[22:25]
	v_mfma_f32_16x16x32_bf16 v[18:21], v[222:225], v[190:193], v[18:21]
	v_mfma_f32_16x16x32_bf16 v[14:17], v[214:217], v[198:201], v[14:17]
	v_mfma_f32_16x16x32_bf16 v[10:13], v[222:225], v[198:201], v[10:13]
	v_mfma_f32_16x16x32_bf16 v[6:9], v[214:217], v[206:209], v[6:9]
	v_mfma_f32_16x16x32_bf16 v[2:5], v[222:225], v[206:209], v[2:5]
	v_mfma_f32_16x16x32_bf16 v[30:33], v[218:221], v[186:189], v[30:33]
	v_mfma_f32_16x16x32_bf16 v[26:29], v[226:229], v[186:189], v[26:29]
	v_mfma_f32_16x16x32_bf16 v[22:25], v[218:221], v[194:197], v[22:25]
	v_mfma_f32_16x16x32_bf16 v[18:21], v[226:229], v[194:197], v[18:21]
	v_mfma_f32_16x16x32_bf16 v[14:17], v[218:221], v[202:205], v[14:17]
	v_mfma_f32_16x16x32_bf16 v[10:13], v[226:229], v[202:205], v[10:13]
	v_mfma_f32_16x16x32_bf16 v[6:9], v[218:221], v[210:213], v[6:9]
	v_mfma_f32_16x16x32_bf16 v[2:5], v[226:229], v[210:213], v[2:5]
	s_setprio 0
	s_add_i32 s15, s15, 2
	s_cmp_lt_u32 s15, 12
	s_barrier
	s_cbranch_scc1 .LBB0_884
	v_readfirstlane_b32 s42, v170
	v_readfirstlane_b32 s98, v171
	s_mov_b32 s99, 0
	s_nop 1
	s_lshl_b32 s42, s42, 4
	s_add_i32 s98, s98, s3
	s_cmpk_gt_i32 s98, 0x57f
	s_cbranch_scc1 .Lup1_noearly
	s_mul_hi_i32 s43, s98, 0x2e8ba2e9
	s_lshr_b32 s44, s43, 31
	s_ashr_i32 s43, s43, 5
	s_add_i32 s43, s43, s44
	s_mul_i32 s44, s43, 0xb0
	s_sub_i32 s44, s98, s44
	s_lshl_b32 s43, s43, 3
	s_and_b32 s45, s44, 7
	s_or_b32 s43, s45, s43
	s_ashr_i32 s44, s44, 3
	s_lshl_b32 s43, s43, 19
	s_lshl_b32 s44, s44, 19
	s_add_u32 s100, s26, s43
	s_addc_u32 s101, s27, 0
	s_add_u32 s98, s24, s44
	s_addc_u32 s99, s25, 0
.Lup1_noearly:
	v_lshl_add_u64 v[198:199], s[12:13], 0, v[130:131]
	v_readfirstlane_b32 s15, v144
	v_lshl_add_u64 v[198:199], v[198:199], 0, s[6:7]
	s_mov_b32 m0, s15
	v_lshl_add_u64 v[132:133], s[12:13], 0, v[132:133]
	v_readfirstlane_b32 s12, v143
	ds_read_b128 v[146:149], v145
	ds_read_b128 v[150:153], v145 offset:1024
	ds_read_b128 v[154:157], v145 offset:2048
	ds_read_b128 v[158:161], v145 offset:3072
	ds_read_b128 v[162:165], v139
	ds_read_b128 v[166:169], v139 offset:1024
	ds_read_b128 v[174:177], v138
	ds_read_b128 v[178:181], v138 offset:1024
	ds_read_b128 v[182:185], v137
	ds_read_b128 v[186:189], v137 offset:1024
	ds_read_b128 v[190:193], v136
	ds_read_b128 v[194:197], v136 offset:1024
	global_load_lds_dwordx4 v[198:199], off
	v_lshl_add_u64 v[132:133], v[132:133], 0, s[6:7]
	s_mov_b32 m0, s12
	s_nop 0
	global_load_lds_dwordx4 v[132:133], off
	s_waitcnt vmcnt(10)
	s_barrier
	s_waitcnt lgkmcnt(0)
	s_setprio 1
	s_waitcnt lgkmcnt(0)
	v_mfma_f32_16x16x32_bf16 v[126:129], v[146:149], v[162:165], v[126:129]
	v_mfma_f32_16x16x32_bf16 v[122:125], v[154:157], v[162:165], v[122:125]
	v_mfma_f32_16x16x32_bf16 v[110:113], v[146:149], v[182:185], v[110:113]
	v_mfma_f32_16x16x32_bf16 v[106:109], v[154:157], v[182:185], v[106:109]
	v_mfma_f32_16x16x32_bf16 v[126:129], v[150:153], v[166:169], v[126:129]
	v_mfma_f32_16x16x32_bf16 v[122:125], v[158:161], v[166:169], v[122:125]
	v_mfma_f32_16x16x32_bf16 v[118:121], v[146:149], v[174:177], v[118:121]
	v_mfma_f32_16x16x32_bf16 v[114:117], v[154:157], v[174:177], v[114:117]
	v_mfma_f32_16x16x32_bf16 v[110:113], v[150:153], v[186:189], v[110:113]
	v_mfma_f32_16x16x32_bf16 v[106:109], v[158:161], v[186:189], v[106:109]
	v_mfma_f32_16x16x32_bf16 v[102:105], v[146:149], v[190:193], v[102:105]
	v_mfma_f32_16x16x32_bf16 v[98:101], v[154:157], v[190:193], v[98:101]
	v_mfma_f32_16x16x32_bf16 v[198:201], v[150:153], v[178:181], v[118:121]
	v_mfma_f32_16x16x32_bf16 v[202:205], v[158:161], v[178:181], v[114:117]
	v_mfma_f32_16x16x32_bf16 v[206:209], v[150:153], v[194:197], v[102:105]
	v_mfma_f32_16x16x32_bf16 v[210:213], v[158:161], v[194:197], v[98:101]
	s_setprio 0
	s_barrier
; #define GAS __attribute__((address_space(1)))
; __device__ __forceinline__ int otid() { int t = threadIdx.x; asm volatile("" : "+v"(t)); return t; }
; #define STAGE(P, GP, ktrel) do { const GAS char* _g = (GP) + (ktrel) * (BK * 2); \
;     __builtin_amdgcn_global_load_lds((const GAS unsigned*)(_g + so0), (unsigned*)((char*)(P) + tid_ * 16), 16, 0, 0); \
;     __builtin_amdgcn_global_load_lds((const GAS unsigned*)(_g + so1), (unsigned*)((char*)(P) + tid_ * 16 + 8192), 16, 0, 0); } while (0)
; #define WAIT_V(n) asm volatile("s_waitcnt vmcnt(" #n ")" ::: "memory")
; #define WAIT_L(n) asm volatile("s_waitcnt lgkmcnt(" #n ")" ::: "memory")
; #define BAR __builtin_amdgcn_s_barrier()
; template <int K, int LD = K>
; __device__ __forceinline__ void gemm_prefetch(const GAS bf16* A, const GAS bf16* Bt, int brow, int bcol) {
;   bf16* shm = (bf16*)smem_raw;
;   const int tid_ = otid();
;   unsigned so0, so1;
;   { int r_, c_; stage_rc(tid_ * 16, r_, c_); so0 = (unsigned)(r_ * LD + c_) * 2u; stage_rc(tid_ * 16 + 8192, r_, c_); so1 = (unsigned)(r_ * LD + c_) * 2u; }
;   const GAS char* pA0 = (const GAS char*)A + (long)brow * LD * 2; const GAS char* pA1 = pA0 + (long)HALF * LD * 2;
;   const GAS char* pB0 = (const GAS char*)Bt + (long)bcol * LD * 2; const GAS char* pB1 = pB0 + (long)HALF * LD * 2;
;   asm volatile("" : "+s"(pA0), "+s"(pA1), "+s"(pB0), "+s"(pB1));
;   STAGE(SB(0, 0), pB0, 0); STAGE(SA(0, 0), pA0, 0);
;   STAGE(SB(0, 1), pB1, 0); STAGE(SA(0, 1), pA1, 0);
;   STAGE(SB(1, 0), pB0, 1); STAGE(SA(1, 0), pA0, 1); STAGE(SB(1, 1), pB1, 1);
; }
; template <int K, int LD = K>
; __device__ __forceinline__ void gemm_main(const GAS bf16* A, const GAS bf16* Bt, int brow, int bcol, f32x4 (&acc)[2][2][4][2]) {
;     ...
;   { LDB(B0, 0, 0); LDA(At, 0, 0); STAGE(SA(1, 1), pA1, 1);
;     BAR; WAIT_L(0); MMA(0, 0, At, B0); BAR;
;     LDB(B1, 0, 1); BAR; WAIT_L(0); MMA(0, 1, At, B1); BAR;
;     LDA(At, 0, 1); WAIT_V(4); BAR; WAIT_L(0); MMA(1, 0, At, B0); MMA(1, 1, At, B1); BAR; }
;   { LDB(B0, 1, 0); LDA(At, 1, 0); WAIT_V(2); BAR; WAIT_L(0); MMA(0, 0, At, B0); BAR;
;     LDB(B1, 1, 1); WAIT_V(0); BAR; WAIT_L(0); MMA(0, 1, At, B1); BAR;
;     LDA(At, 1, 1); BAR; WAIT_L(0); MMA(1, 0, At, B0); MMA(1, 1, At, B1); BAR; }
	s_nop 1
	ds_read_b128 v[98:101], v142
	ds_read_b128 v[102:105], v142 offset:1024
	ds_read_b128 v[114:117], v142 offset:2048
	ds_read_b128 v[118:121], v142 offset:3072
	s_waitcnt vmcnt(8)
	s_barrier
	s_waitcnt lgkmcnt(0)
	s_setprio 1
	s_waitcnt lgkmcnt(0)
	v_mfma_f32_16x16x32_bf16 v[94:97], v[98:101], v[162:165], v[94:97]
	v_mfma_f32_16x16x32_bf16 v[90:93], v[114:117], v[162:165], v[90:93]
	v_mfma_f32_16x16x32_bf16 v[78:81], v[98:101], v[182:185], v[78:81]
	v_mfma_f32_16x16x32_bf16 v[74:77], v[114:117], v[182:185], v[74:77]
	v_mfma_f32_16x16x32_bf16 v[94:97], v[102:105], v[166:169], v[94:97]
	v_mfma_f32_16x16x32_bf16 v[90:93], v[118:121], v[166:169], v[90:93]
	v_mfma_f32_16x16x32_bf16 v[86:89], v[98:101], v[174:177], v[86:89]
	v_mfma_f32_16x16x32_bf16 v[82:85], v[114:117], v[174:177], v[82:85]
	v_mfma_f32_16x16x32_bf16 v[78:81], v[102:105], v[186:189], v[78:81]
	v_mfma_f32_16x16x32_bf16 v[74:77], v[118:121], v[186:189], v[74:77]
	v_mfma_f32_16x16x32_bf16 v[70:73], v[98:101], v[190:193], v[70:73]
	v_mfma_f32_16x16x32_bf16 v[66:69], v[114:117], v[190:193], v[66:69]
	v_mfma_f32_16x16x32_bf16 v[142:145], v[102:105], v[178:181], v[86:89]
	v_mfma_f32_16x16x32_bf16 v[162:165], v[118:121], v[178:181], v[82:85]
	v_mfma_f32_16x16x32_bf16 v[166:169], v[102:105], v[194:197], v[70:73]
	v_mfma_f32_16x16x32_bf16 v[174:177], v[118:121], v[194:197], v[66:69]
	s_setprio 0
	s_barrier
	s_nop 1
	ds_read_b128 v[66:69], v139 offset:16384
	ds_read_b128 v[70:73], v139 offset:17408
	ds_read_b128 v[82:85], v138 offset:16384
	ds_read_b128 v[86:89], v138 offset:17408
	ds_read_b128 v[178:181], v137 offset:16384
	ds_read_b128 v[182:185], v137 offset:17408
	ds_read_b128 v[186:189], v136 offset:16384
	ds_read_b128 v[190:193], v136 offset:17408
	s_waitcnt vmcnt(4)
	s_barrier
	s_waitcnt lgkmcnt(0)
	s_setprio 1
	s_waitcnt lgkmcnt(0)
	v_mfma_f32_16x16x32_bf16 v[62:65], v[146:149], v[66:69], v[62:65]
	v_mfma_f32_16x16x32_bf16 v[58:61], v[154:157], v[66:69], v[58:61]
	v_mfma_f32_16x16x32_bf16 v[46:49], v[146:149], v[178:181], v[46:49]
	v_mfma_f32_16x16x32_bf16 v[38:41], v[146:149], v[186:189], v[38:41]
	v_mfma_f32_16x16x32_bf16 v[62:65], v[150:153], v[70:73], v[62:65]
	v_mfma_f32_16x16x32_bf16 v[58:61], v[158:161], v[70:73], v[58:61]
	v_mfma_f32_16x16x32_bf16 v[54:57], v[146:149], v[82:85], v[54:57]
	v_mfma_f32_16x16x32_bf16 v[50:53], v[154:157], v[82:85], v[50:53]
	v_mfma_f32_16x16x32_bf16 v[46:49], v[150:153], v[182:185], v[46:49]
	v_mfma_f32_16x16x32_bf16 v[42:45], v[154:157], v[178:181], v[42:45]
	v_mfma_f32_16x16x32_bf16 v[38:41], v[150:153], v[190:193], v[38:41]
	v_mfma_f32_16x16x32_bf16 v[34:37], v[154:157], v[186:189], v[34:37]
	v_mfma_f32_16x16x32_bf16 v[194:197], v[150:153], v[86:89], v[54:57]
	v_mfma_f32_16x16x32_bf16 v[214:217], v[158:161], v[86:89], v[50:53]
	v_mfma_f32_16x16x32_bf16 v[218:221], v[158:161], v[182:185], v[42:45]
	v_mfma_f32_16x16x32_bf16 v[146:149], v[158:161], v[190:193], v[34:37]
	s_setprio 0
	s_setprio 1
	v_mfma_f32_16x16x32_bf16 v[30:33], v[98:101], v[66:69], v[30:33]
	v_mfma_f32_16x16x32_bf16 v[26:29], v[114:117], v[66:69], v[26:29]
	v_mfma_f32_16x16x32_bf16 v[14:17], v[98:101], v[178:181], v[14:17]
	v_mfma_f32_16x16x32_bf16 v[6:9], v[98:101], v[186:189], v[6:9]
	v_mfma_f32_16x16x32_bf16 v[30:33], v[102:105], v[70:73], v[30:33]
	v_mfma_f32_16x16x32_bf16 v[26:29], v[118:121], v[70:73], v[26:29]
	v_mfma_f32_16x16x32_bf16 v[22:25], v[98:101], v[82:85], v[22:25]
	v_mfma_f32_16x16x32_bf16 v[18:21], v[114:117], v[82:85], v[18:21]
	v_mfma_f32_16x16x32_bf16 v[14:17], v[102:105], v[182:185], v[14:17]
	v_mfma_f32_16x16x32_bf16 v[10:13], v[114:117], v[178:181], v[10:13]
	v_mfma_f32_16x16x32_bf16 v[6:9], v[102:105], v[190:193], v[6:9]
	v_mfma_f32_16x16x32_bf16 v[2:5], v[114:117], v[186:189], v[2:5]
	v_mfma_f32_16x16x32_bf16 v[150:153], v[102:105], v[86:89], v[22:25]
	v_mfma_f32_16x16x32_bf16 v[154:157], v[118:121], v[86:89], v[18:21]
	v_mfma_f32_16x16x32_bf16 v[158:161], v[118:121], v[182:185], v[10:13]
	v_mfma_f32_16x16x32_bf16 v[178:181], v[118:121], v[190:193], v[2:5]
	s_setprio 0
	s_barrier
	s_nop 1
	ds_read_b128 v[2:5], v141
	ds_read_b128 v[10:13], v141 offset:1024
	ds_read_b128 v[182:185], v141 offset:2048
	ds_read_b128 v[186:189], v141 offset:3072
	ds_read_b128 v[18:21], v139 offset:32768
	ds_read_b128 v[22:25], v139 offset:33792
	ds_read_b128 v[34:37], v138 offset:32768
	ds_read_b128 v[42:45], v138 offset:33792
	ds_read_b128 v[50:53], v137 offset:32768
	ds_read_b128 v[54:57], v137 offset:33792
	ds_read_b128 v[190:193], v136 offset:32768
	ds_read_b128 v[222:225], v136 offset:33792
	s_waitcnt vmcnt(2)
	s_barrier
	s_waitcnt lgkmcnt(0)
	s_setprio 1
	s_waitcnt lgkmcnt(0)
	v_mfma_f32_16x16x32_bf16 v[66:69], v[2:5], v[18:21], v[126:129]
	v_mfma_f32_16x16x32_bf16 v[118:121], v[10:13], v[22:25], v[66:69]
	v_mfma_f32_16x16x32_bf16 v[66:69], v[182:185], v[18:21], v[122:125]
	v_mfma_f32_16x16x32_bf16 v[114:117], v[186:189], v[22:25], v[66:69]
	v_mfma_f32_16x16x32_bf16 v[66:69], v[2:5], v[34:37], v[198:201]
	v_mfma_f32_16x16x32_bf16 v[102:105], v[10:13], v[42:45], v[66:69]
	v_mfma_f32_16x16x32_bf16 v[66:69], v[182:185], v[34:37], v[202:205]
	v_mfma_f32_16x16x32_bf16 v[98:101], v[186:189], v[42:45], v[66:69]
	v_mfma_f32_16x16x32_bf16 v[66:69], v[2:5], v[50:53], v[110:113]
	v_mfma_f32_16x16x32_bf16 v[86:89], v[10:13], v[54:57], v[66:69]
	v_mfma_f32_16x16x32_bf16 v[66:69], v[182:185], v[50:53], v[106:109]
	v_mfma_f32_16x16x32_bf16 v[82:85], v[186:189], v[54:57], v[66:69]
	v_mfma_f32_16x16x32_bf16 v[66:69], v[2:5], v[190:193], v[206:209]
	v_mfma_f32_16x16x32_bf16 v[70:73], v[10:13], v[222:225], v[66:69]
	v_mfma_f32_16x16x32_bf16 v[66:69], v[182:185], v[190:193], v[210:213]
	v_mfma_f32_16x16x32_bf16 v[66:69], v[186:189], v[222:225], v[66:69]
	s_setprio 0
	s_barrier
	ds_read_b128 v[198:201], v140
	ds_read_b128 v[202:205], v140 offset:1024
	ds_read_b128 v[206:209], v140 offset:2048
	ds_read_b128 v[210:213], v140 offset:3072
	s_waitcnt vmcnt(0)
	s_cmp_eq_u32 s99, 0
	s_cbranch_scc1 .Lup1_early2_skip
	s_add_i32 s43, s42, 0x10100
	s_mov_b32 m0, s43
	s_nop 0
	global_load_lds_dwordx4 v130, s[98:99]
	s_add_u32 s98, s98, 0x20000
	s_addc_u32 s99, s99, 0
	s_add_i32 s43, s42, 0x12100
	s_mov_b32 m0, s43
	s_nop 0
	global_load_lds_dwordx4 v130, s[98:99]
	s_add_i32 s43, s42, 0x100
	s_mov_b32 m0, s43
	s_nop 0
	global_load_lds_dwordx4 v130, s[100:101]
	s_add_u32 s100, s100, 0x20000
	s_addc_u32 s101, s101, 0
	s_add_i32 s43, s42, 0x2100
	s_mov_b32 m0, s43
	s_nop 0
	global_load_lds_dwordx4 v130, s[100:101]
